# stack + conversion prologue stores write-through (clean L2 at the global barrier and at the set-1 publish)
# baseline (speedup 1.0000x reference)
.LBB0_19:
	ds_write2_b32 v24, v15, v25 offset1:66
	ds_write2_b32 v24, v26, v27 offset0:132 offset1:198
	ds_write2_b32 v56, v28, v29 offset0:8 offset1:74
	ds_write2_b32 v56, v30, v31 offset0:140 offset1:206
	ds_write2_b32 v57, v32, v33 offset0:16 offset1:82
	ds_write2_b32 v57, v34, v35 offset0:148 offset1:214
	ds_write2_b32 v58, v36, v37 offset0:24 offset1:90
	ds_write2_b32 v58, v38, v39 offset0:156 offset1:222
	ds_write2_b32 v59, v40, v41 offset0:32 offset1:98
	ds_write2_b32 v59, v42, v43 offset0:164 offset1:230
	ds_write2_b32 v60, v44, v45 offset0:40 offset1:106
	ds_write2_b32 v60, v46, v47 offset0:172 offset1:238
	ds_write2_b32 v61, v55, v54 offset0:48 offset1:114
	ds_write2_b32 v61, v53, v52 offset0:180 offset1:246
	ds_write2_b32 v62, v51, v50 offset0:56 offset1:122
	ds_write2_b32 v62, v49, v48 offset0:188 offset1:254
	s_waitcnt lgkmcnt(0)
	ds_read2_b32 v[60:61], v20 offset1:8
	ds_read2_b32 v[62:63], v20 offset0:33 offset1:41
	ds_read2_b32 v[64:65], v20 offset0:66 offset1:74
	ds_read2_b32 v[66:67], v20 offset0:99 offset1:107
	ds_read2_b32 v[68:69], v20 offset0:132 offset1:140
	ds_read2_b32 v[70:71], v20 offset0:165 offset1:173
	ds_read2_b32 v[72:73], v20 offset0:198 offset1:206
	ds_read2_b32 v[74:75], v20 offset0:231 offset1:239
	s_mul_i32 s29, s29, s28
	s_waitcnt vmcnt(0) lgkmcnt(7)
	v_mul_f32_e32 v56, v6, v60
	s_waitcnt lgkmcnt(6)
	v_mul_f32_e32 v57, v7, v62
	s_sub_i32 s14, s14, s29
	v_cvt_pk_bf16_f32 v56, v56, v57
	s_waitcnt lgkmcnt(5)
	v_mul_f32_e32 v57, v8, v64
	s_waitcnt lgkmcnt(4)
	v_mul_f32_e32 v58, v9, v66
	s_sext_i32_i16 s28, s14
	v_cvt_pk_bf16_f32 v57, v57, v58
	s_waitcnt lgkmcnt(3)
	v_mul_f32_e32 v58, v2, v68
	s_waitcnt lgkmcnt(2)
	v_mul_f32_e32 v59, v3, v70
	s_lshl_b32 s30, s28, 5
	v_cvt_pk_bf16_f32 v58, v58, v59
	s_waitcnt lgkmcnt(1)
	v_mul_f32_e32 v59, v4, v72
	s_waitcnt lgkmcnt(0)
	v_mul_f32_e32 v60, v5, v74
	v_cvt_pk_bf16_f32 v59, v59, v60
	v_or_b32_e32 v60, s30, v19
	v_mad_u64_u32 v[76:77], s[28:29], v60, s31, 0
	s_bfe_i64 s[28:29], s[14:15], 0x100000
	s_mul_i32 s14, s29, s31
	v_add_u32_e32 v77, s14, v77
	v_lshl_add_u64 v[76:77], v[76:77], 1, s[38:39]
	s_lshl_b64 s[26:27], s[26:27], 1
	v_lshl_add_u64 v[76:77], v[76:77], 0, s[26:27]
	v_lshl_add_u64 v[76:77], v[76:77], 0, v[10:11]
	global_store_dwordx4 v[76:77], v[56:59], off sc1
	v_mul_f32_e32 v60, v5, v75
	s_nop 0
	v_mul_f32_e32 v56, v6, v61
	v_mul_f32_e32 v57, v7, v63
	v_cvt_pk_bf16_f32 v56, v56, v57
	v_mul_f32_e32 v57, v8, v65
	v_mul_f32_e32 v58, v9, v67
	v_cvt_pk_bf16_f32 v57, v57, v58
	v_mul_f32_e32 v58, v2, v69
	v_mul_f32_e32 v59, v3, v71
	v_cvt_pk_bf16_f32 v58, v58, v59
	v_mul_f32_e32 v59, v4, v73
	v_cvt_pk_bf16_f32 v59, v59, v60
	v_or_b32_e32 v60, s30, v21
	v_mad_u64_u32 v[60:61], s[28:29], v60, s31, 0
	v_add_u32_e32 v61, s14, v61
	v_lshl_add_u64 v[60:61], v[60:61], 1, s[38:39]
	v_lshl_add_u64 v[60:61], v[60:61], 0, s[26:27]
	v_lshl_add_u64 v[60:61], v[60:61], 0, v[10:11]
	ds_read2_b32 v[62:63], v20 offset0:16 offset1:24
	ds_read2_b32 v[64:65], v20 offset0:49 offset1:57
	global_store_dwordx4 v[60:61], v[56:59], off sc1
	ds_read2_b32 v[60:61], v20 offset0:82 offset1:90
	ds_read2_b32 v[66:67], v20 offset0:115 offset1:123
	ds_read2_b32 v[68:69], v20 offset0:148 offset1:156
	ds_read2_b32 v[70:71], v20 offset0:181 offset1:189
	ds_read2_b32 v[72:73], v20 offset0:214 offset1:222
	ds_read2_b32 v[74:75], v20 offset0:247 offset1:255
	s_waitcnt lgkmcnt(7)
	v_mul_f32_e32 v56, v6, v62
	s_waitcnt lgkmcnt(6)
	v_mul_f32_e32 v57, v7, v64
	v_cvt_pk_bf16_f32 v56, v56, v57
	s_waitcnt lgkmcnt(5)
	v_mul_f32_e32 v57, v8, v60
	s_waitcnt lgkmcnt(4)
	v_mul_f32_e32 v58, v9, v66
	v_mul_f32_e32 v6, v6, v63
	v_mul_f32_e32 v7, v7, v65
	v_cvt_pk_bf16_f32 v57, v57, v58
	s_waitcnt lgkmcnt(3)
	v_mul_f32_e32 v58, v2, v68
	s_waitcnt lgkmcnt(2)
	v_mul_f32_e32 v59, v3, v70
	v_cvt_pk_bf16_f32 v6, v6, v7
	v_mul_f32_e32 v7, v8, v61
	v_mul_f32_e32 v8, v9, v67
	v_mul_f32_e32 v2, v2, v69
	v_cvt_pk_bf16_f32 v58, v58, v59
	s_waitcnt lgkmcnt(1)
	v_mul_f32_e32 v59, v4, v72
	s_waitcnt lgkmcnt(0)
	v_mul_f32_e32 v60, v5, v74
	v_cvt_pk_bf16_f32 v7, v7, v8
	v_mul_f32_e32 v3, v3, v71
	v_cvt_pk_bf16_f32 v8, v2, v3
	v_mul_f32_e32 v2, v4, v73
	v_cvt_pk_bf16_f32 v59, v59, v60
	v_or_b32_e32 v60, s30, v22
	v_mul_f32_e32 v3, v5, v75
	v_cvt_pk_bf16_f32 v9, v2, v3
	v_or_b32_e32 v2, s30, v23
	v_mad_u64_u32 v[76:77], s[28:29], v60, s31, 0
	v_mad_u64_u32 v[2:3], s[28:29], v2, s31, 0
	v_add_u32_e32 v77, s14, v77
	v_add_u32_e32 v3, s14, v3
	v_lshl_add_u64 v[76:77], v[76:77], 1, s[38:39]
	v_lshl_add_u64 v[2:3], v[2:3], 1, s[38:39]
	v_lshl_add_u64 v[76:77], v[76:77], 0, s[26:27]
	v_lshl_add_u64 v[2:3], v[2:3], 0, s[26:27]
	v_lshl_add_u64 v[76:77], v[76:77], 0, v[10:11]
	v_lshl_add_u64 v[2:3], v[2:3], 0, v[10:11]
	global_store_dwordx4 v[76:77], v[56:59], off sc1
	global_store_dwordx4 v[2:3], v[6:9], off sc1
	s_waitcnt lgkmcnt(0)

.LBB0_88:
	s_waitcnt vmcnt(30)
	ds_write2_b32 v24, v56, v57 offset1:66
	s_waitcnt vmcnt(28)
	ds_write2_b32 v24, v58, v60 offset0:132 offset1:198
	v_add_u32_e32 v56, 0x400, v24
	s_waitcnt vmcnt(26)
	ds_write2_b32 v56, v59, v61 offset0:8 offset1:74
	s_waitcnt vmcnt(24)
	ds_write2_b32 v56, v62, v63 offset0:140 offset1:206
	v_add_u32_e32 v57, 0x800, v24
	v_add_u32_e32 v58, 0xc00, v24
	v_add_u32_e32 v59, 0x1000, v24
	v_add_u32_e32 v60, 0x1400, v24
	v_add_u32_e32 v61, 0x1800, v24
	v_add_u32_e32 v62, 0x1c00, v24
	s_waitcnt vmcnt(22)
	ds_write2_b32 v57, v64, v65 offset0:16 offset1:82
	s_waitcnt vmcnt(20)
	ds_write2_b32 v57, v66, v68 offset0:148 offset1:214
	s_waitcnt vmcnt(18)
	ds_write2_b32 v58, v67, v69 offset0:24 offset1:90
	s_waitcnt vmcnt(16)
	ds_write2_b32 v58, v70, v71 offset0:156 offset1:222
	s_waitcnt vmcnt(14)
	ds_write2_b32 v59, v72, v73 offset0:32 offset1:98
	s_waitcnt vmcnt(12)
	ds_write2_b32 v59, v74, v76 offset0:164 offset1:230
	s_waitcnt vmcnt(10)
	ds_write2_b32 v60, v75, v77 offset0:40 offset1:106
	s_waitcnt vmcnt(8)
	ds_write2_b32 v60, v78, v79 offset0:172 offset1:238
	s_waitcnt vmcnt(6)
	ds_write2_b32 v61, v80, v81 offset0:48 offset1:114
	s_waitcnt vmcnt(4)
	ds_write2_b32 v61, v82, v84 offset0:180 offset1:246
	s_waitcnt vmcnt(2)
	ds_write2_b32 v62, v83, v85 offset0:56 offset1:122
	s_waitcnt vmcnt(0)
	ds_write2_b32 v62, v86, v87 offset0:188 offset1:254
	s_waitcnt lgkmcnt(0)
	ds_read2_b32 v[68:69], v20 offset1:8
	ds_read2_b32 v[70:71], v20 offset0:33 offset1:41
	ds_read2_b32 v[72:73], v20 offset0:66 offset1:74
	ds_read2_b32 v[74:75], v20 offset0:99 offset1:107
	ds_read2_b32 v[76:77], v20 offset0:132 offset1:140
	ds_read2_b32 v[78:79], v20 offset0:165 offset1:173
	ds_read2_b32 v[80:81], v20 offset0:198 offset1:206
	ds_read2_b32 v[82:83], v20 offset0:231 offset1:239
	s_waitcnt lgkmcnt(7)
	v_mul_f32_e32 v63, v6, v68
	s_waitcnt lgkmcnt(6)
	v_mul_f32_e32 v64, v7, v70
	v_cvt_pk_bf16_f32 v64, v63, v64
	s_waitcnt lgkmcnt(5)
	v_mul_f32_e32 v63, v8, v72
	s_waitcnt lgkmcnt(4)
	v_mul_f32_e32 v65, v9, v74
	v_cvt_pk_bf16_f32 v65, v63, v65
	s_waitcnt lgkmcnt(3)
	v_mul_f32_e32 v63, v2, v76
	s_waitcnt lgkmcnt(2)
	v_mul_f32_e32 v66, v3, v78
	v_cvt_pk_bf16_f32 v66, v63, v66
	s_waitcnt lgkmcnt(1)
	v_mul_f32_e32 v63, v4, v80
	s_waitcnt lgkmcnt(0)
	v_mul_f32_e32 v67, v5, v82
	v_cvt_pk_bf16_f32 v67, v63, v67
	v_or_b32_e32 v63, s30, v19
	v_mul_hi_i32_i24_e32 v85, s59, v63
	v_mul_i32_i24_e32 v84, s59, v63
	v_lshl_add_u64 v[84:85], v[84:85], 1, s[26:27]
	s_lshl_b64 s[28:29], s[34:35], 1
	v_lshl_add_u64 v[84:85], v[84:85], 0, s[28:29]
	v_lshl_add_u64 v[84:85], v[84:85], 0, v[10:11]
	global_store_dwordx4 v[84:85], v[64:67], off sc1
	v_mul_f32_e32 v63, v6, v69
	s_andn2_b64 vcc, exec, s[36:37]
	v_mul_f32_e32 v64, v7, v71
	v_cvt_pk_bf16_f32 v64, v63, v64
	v_mul_f32_e32 v63, v8, v73
	v_mul_f32_e32 v65, v9, v75
	v_cvt_pk_bf16_f32 v65, v63, v65
	v_mul_f32_e32 v63, v2, v77
	v_mul_f32_e32 v66, v3, v79
	v_cvt_pk_bf16_f32 v66, v63, v66
	v_mul_f32_e32 v63, v4, v81
	v_mul_f32_e32 v67, v5, v83
	v_cvt_pk_bf16_f32 v67, v63, v67
	v_or_b32_e32 v63, s30, v21
	v_mul_hi_i32_i24_e32 v69, s59, v63
	v_mul_i32_i24_e32 v68, s59, v63
	v_lshl_add_u64 v[68:69], v[68:69], 1, s[26:27]
	v_lshl_add_u64 v[68:69], v[68:69], 0, s[28:29]
	v_lshl_add_u64 v[68:69], v[68:69], 0, v[10:11]
	ds_read2_b32 v[70:71], v20 offset0:16 offset1:24
	ds_read2_b32 v[72:73], v20 offset0:49 offset1:57
	global_store_dwordx4 v[68:69], v[64:67], off sc1
	ds_read2_b32 v[68:69], v20 offset0:82 offset1:90
	ds_read2_b32 v[74:75], v20 offset0:115 offset1:123
	ds_read2_b32 v[76:77], v20 offset0:148 offset1:156
	ds_read2_b32 v[78:79], v20 offset0:181 offset1:189
	ds_read2_b32 v[80:81], v20 offset0:214 offset1:222
	ds_read2_b32 v[82:83], v20 offset0:247 offset1:255
	s_waitcnt lgkmcnt(7)
	v_mul_f32_e32 v63, v6, v70
	s_waitcnt lgkmcnt(6)
	v_mul_f32_e32 v64, v7, v72
	v_cvt_pk_bf16_f32 v64, v63, v64
	s_waitcnt lgkmcnt(5)
	v_mul_f32_e32 v63, v8, v68
	s_waitcnt lgkmcnt(4)
	v_mul_f32_e32 v65, v9, v74
	v_mul_f32_e32 v6, v6, v71
	v_mul_f32_e32 v7, v7, v73
	v_cvt_pk_bf16_f32 v65, v63, v65
	s_waitcnt lgkmcnt(3)
	v_mul_f32_e32 v63, v2, v76
	s_waitcnt lgkmcnt(2)
	v_mul_f32_e32 v66, v3, v78
	v_cvt_pk_bf16_f32 v6, v6, v7
	v_mul_f32_e32 v7, v8, v69
	v_mul_f32_e32 v8, v9, v75
	v_mul_f32_e32 v2, v2, v77
	v_cvt_pk_bf16_f32 v66, v63, v66
	s_waitcnt lgkmcnt(1)
	v_mul_f32_e32 v63, v4, v80
	s_waitcnt lgkmcnt(0)
	v_mul_f32_e32 v67, v5, v82
	v_cvt_pk_bf16_f32 v7, v7, v8
	v_mul_f32_e32 v3, v3, v79
	v_cvt_pk_bf16_f32 v8, v2, v3
	v_mul_f32_e32 v2, v4, v81
	v_cvt_pk_bf16_f32 v67, v63, v67
	v_or_b32_e32 v63, s30, v22
	v_mul_f32_e32 v3, v5, v83
	v_cvt_pk_bf16_f32 v9, v2, v3
	v_or_b32_e32 v2, s30, v23
	v_mul_hi_i32_i24_e32 v85, s59, v63
	v_mul_i32_i24_e32 v84, s59, v63
	v_mul_hi_i32_i24_e32 v3, s59, v2
	v_mul_i32_i24_e32 v2, s59, v2
	v_lshl_add_u64 v[84:85], v[84:85], 1, s[26:27]
	v_lshl_add_u64 v[2:3], v[2:3], 1, s[26:27]
	v_lshl_add_u64 v[84:85], v[84:85], 0, s[28:29]
	v_lshl_add_u64 v[2:3], v[2:3], 0, s[28:29]
	v_lshl_add_u64 v[84:85], v[84:85], 0, v[10:11]
	v_lshl_add_u64 v[2:3], v[2:3], 0, v[10:11]
	global_store_dwordx4 v[84:85], v[64:67], off sc1
	global_store_dwordx4 v[2:3], v[6:9], off sc1
	s_waitcnt lgkmcnt(0)
	s_cbranch_vccnz .LBB0_20
	s_lshr_b32 s28, s60, 5
	v_cvt_f32_i32_e32 v2, s28
	s_sext_i32_i16 s26, s14
	v_cvt_f32_i32_e32 v3, s26
	s_ashr_i32 s26, s26, 30
	v_rcp_iflag_f32_e32 v4, v2
	s_or_b32 s29, s26, 1
	v_mul_f32_e32 v4, v3, v4
	v_trunc_f32_e32 v4, v4
	v_fma_f32 v3, -v4, v2, v3
	v_cvt_i32_f32_e32 v4, v4
	v_cmp_ge_f32_e64 s[26:27], |v3|, v2
	s_and_b64 s[26:27], s[26:27], exec
	s_cselect_b32 s26, s29, 0
	v_readfirstlane_b32 s29, v4
	s_add_i32 s29, s29, s26
	s_sext_i32_i16 s26, s29
	s_lshl_b32 s26, s26, 6
	s_ashr_i32 s27, s26, 31
	s_cmp_eq_u64 s[40:41], 0
	s_cbranch_scc0 .LBB0_18
	v_mov_b32_e32 v2, 1.0
	v_mov_b32_e32 v3, 1.0
	v_mov_b32_e32 v4, 1.0
	v_mov_b32_e32 v5, 1.0
	v_mov_b32_e32 v6, 1.0
	v_mov_b32_e32 v7, 1.0
	v_mov_b32_e32 v8, 1.0
	v_mov_b32_e32 v9, 1.0
	s_branch .LBB0_19

.LBB0_94:
	s_mov_b32 s14, 0
	s_mov_b32 s18, 0
	s_ashr_i32 s17, s16, 31
	s_ashr_i32 s19, s18, 31
	s_lshl_b64 s[14:15], s[16:17], 12
	s_lshl_b64 s[18:19], s[18:19], 3
	s_add_u32 s18, s0, s18
	s_addc_u32 s19, s1, s19
	s_load_dwordx2 s[18:19], s[18:19], 0x0
	s_mov_b32 s22, 0
	s_mov_b32 s21, 0
	s_mov_b32 s24, 0
	s_waitcnt lgkmcnt(0)
	s_add_u32 s18, s18, s14
	s_addc_u32 s19, s19, s15
	global_load_dwordx4 v[24:27], v19, s[18:19] nt
	s_mov_b32 s18, 0
	s_ashr_i32 s19, s18, 31
	s_lshl_b64 s[18:19], s[18:19], 3
	s_add_u32 s18, s0, s18
	s_addc_u32 s19, s1, s19
	s_load_dwordx2 s[18:19], s[18:19], 0x0
	s_waitcnt lgkmcnt(0)
	s_add_u32 s18, s18, s14
	s_addc_u32 s19, s19, s15
	global_load_dwordx4 v[28:31], v19, s[18:19] offset:1024 nt
	s_ashr_i32 s23, s22, 31
	s_lshl_b64 s[18:19], s[22:23], 3
	s_add_u32 s18, s0, s18
	s_addc_u32 s19, s1, s19
	s_load_dwordx2 s[18:19], s[18:19], 0x0
	s_mov_b32 s22, 0
	s_waitcnt lgkmcnt(0)
	s_add_u32 s18, s18, s14
	s_addc_u32 s19, s19, s15
	global_load_dwordx4 v[32:35], v19, s[18:19] offset:2048 nt
	s_ashr_i32 s23, s22, 31
	s_lshl_b64 s[18:19], s[22:23], 3
	s_add_u32 s18, s0, s18
	s_addc_u32 s19, s1, s19
	s_load_dwordx2 s[18:19], s[18:19], 0x0
	s_mov_b32 s22, 0
	s_waitcnt lgkmcnt(0)
	s_add_u32 s18, s18, s14
	s_addc_u32 s19, s19, s15
	s_add_i32 s14, s16, s10
	global_load_dwordx4 v[36:39], v19, s[18:19] offset:3072 nt
	s_ashr_i32 s15, s14, 31
	s_ashr_i32 s23, s22, 31
	s_lshl_b64 s[18:19], s[14:15], 12
	s_lshl_b64 s[22:23], s[22:23], 3
	s_add_u32 s22, s0, s22
	s_addc_u32 s23, s1, s23
	s_load_dwordx2 s[22:23], s[22:23], 0x0
	s_waitcnt lgkmcnt(0)
	s_add_u32 s22, s22, s18
	s_addc_u32 s23, s23, s19
	global_load_dwordx4 v[2:5], v19, s[22:23] nt
	s_ashr_i32 s25, s24, 31
	s_lshl_b64 s[22:23], s[24:25], 3
	s_add_u32 s22, s0, s22
	s_addc_u32 s23, s1, s23
	s_load_dwordx2 s[22:23], s[22:23], 0x0
	s_mov_b32 s24, 0
	s_waitcnt lgkmcnt(0)
	s_add_u32 s22, s22, s18
	s_addc_u32 s23, s23, s19
	global_load_dwordx4 v[6:9], v19, s[22:23] offset:1024 nt
	s_ashr_i32 s25, s24, 31
	s_lshl_b64 s[22:23], s[24:25], 3
	s_add_u32 s22, s0, s22
	s_addc_u32 s23, s1, s23
	s_load_dwordx2 s[22:23], s[22:23], 0x0
	s_mov_b32 s24, 0
	s_waitcnt vmcnt(5)
	v_mul_f32_e32 v22, v25, v25
	s_waitcnt lgkmcnt(0)
	s_add_u32 s22, s22, s18
	s_addc_u32 s23, s23, s19
	global_load_dwordx4 v[10:13], v19, s[22:23] offset:2048 nt
	s_ashr_i32 s25, s24, 31
	s_lshl_b64 s[22:23], s[24:25], 3
	s_add_u32 s22, s0, s22
	s_addc_u32 s23, s1, s23
	s_load_dwordx2 s[22:23], s[22:23], 0x0
	v_mul_f32_e32 v23, v27, v27
	v_fmac_f32_e32 v22, v24, v24
	v_fmac_f32_e32 v23, v26, v26
	v_add_f32_e32 v22, v22, v23
	s_waitcnt lgkmcnt(0)
	s_add_u32 s18, s22, s18
	s_addc_u32 s19, s23, s19
	global_load_dwordx4 v[14:17], v19, s[18:19] offset:3072 nt
	s_waitcnt vmcnt(6)
	v_mul_f32_e32 v23, v29, v29
	v_mul_f32_e32 v40, v31, v31
	v_fmac_f32_e32 v23, v28, v28
	v_fmac_f32_e32 v40, v30, v30
	v_add_f32_e32 v23, v23, v40
	v_add_f32_e32 v22, v22, v23
	s_lshl_b64 s[18:19], s[16:17], 11
	v_cvt_pk_bf16_f32 v24, v24, v25
	v_cvt_pk_bf16_f32 v25, v26, v27
	s_waitcnt vmcnt(5)
	v_mul_f32_e32 v23, v33, v33
	v_mul_f32_e32 v40, v35, v35
	v_fmac_f32_e32 v23, v32, v32
	v_fmac_f32_e32 v40, v34, v34
	v_add_f32_e32 v23, v23, v40
	v_add_f32_e32 v22, v22, v23
	s_waitcnt vmcnt(4)
	v_mul_f32_e32 v23, v37, v37
	v_mul_f32_e32 v40, v39, v39
	v_fmac_f32_e32 v23, v36, v36
	v_fmac_f32_e32 v40, v38, v38
	v_add_f32_e32 v23, v23, v40
	v_add_f32_e32 v22, v22, v23
	v_lshl_add_u64 v[40:41], v[20:21], 0, s[18:19]
	global_store_dwordx2 v[40:41], v[24:25], off sc1
	v_add_f32_dpp v22, v22, v22 row_ror:8 row_mask:0xf bank_mask:0xf bound_ctrl:1
	v_cvt_pk_bf16_f32 v24, v28, v29
	v_cvt_pk_bf16_f32 v25, v30, v31
	global_store_dwordx2 v[40:41], v[24:25], off offset:512 sc1
	v_cvt_pk_bf16_f32 v24, v32, v33
	v_cvt_pk_bf16_f32 v25, v34, v35
	s_nop 0
	v_add_f32_dpp v22, v22, v22 row_ror:4 row_mask:0xf bank_mask:0xf bound_ctrl:1
	global_store_dwordx2 v[40:41], v[24:25], off offset:1024 sc1
	v_cvt_pk_bf16_f32 v24, v36, v37
	v_cvt_pk_bf16_f32 v25, v38, v39
	global_store_dwordx2 v[40:41], v[24:25], off offset:1536 sc1
	v_add_f32_dpp v22, v22, v22 row_ror:2 row_mask:0xf bank_mask:0xf bound_ctrl:1
	s_nop 1
	v_add_f32_dpp v22, v22, v22 row_ror:1 row_mask:0xf bank_mask:0xf bound_ctrl:1
	v_mov_b32_e32 v23, v22
	s_nop 1
	v_permlane16_swap_b32_e32 v22, v23
	v_add_f32_e32 v22, v22, v23
	v_mov_b32_e32 v23, v22
	s_nop 1
	v_permlane32_swap_b32_e32 v22, v23
	s_and_saveexec_b64 s[18:19], vcc
	s_cbranch_execz .LBB0_96
	s_ashr_i32 s22, s16, 12
	s_ashr_i32 s23, s22, 31
	s_and_b32 s21, s16, 0xfff
	s_lshl_b64 s[16:17], s[22:23], 18
	s_add_u32 s16, s11, s16
	s_addc_u32 s17, s20, s17
	s_lshl_b32 s21, s21, 2
	v_add_f32_e32 v22, v22, v23
	v_mov_b32_e32 v23, s21
	global_store_dword v23, v22, s[16:17]
.LBB0_96:
	s_or_b64 exec, exec, s[18:19]
	s_waitcnt vmcnt(7)
	v_mul_f32_e32 v22, v3, v3
	v_mul_f32_e32 v23, v5, v5
	v_fmac_f32_e32 v22, v2, v2
	v_fmac_f32_e32 v23, v4, v4
	v_add_f32_e32 v22, v22, v23
	s_waitcnt vmcnt(6)
	v_mul_f32_e32 v23, v7, v7
	v_mul_f32_e32 v24, v9, v9
	v_fmac_f32_e32 v23, v6, v6
	v_fmac_f32_e32 v24, v8, v8
	v_add_f32_e32 v23, v23, v24
	v_add_f32_e32 v22, v22, v23
	s_waitcnt vmcnt(5)
	v_mul_f32_e32 v23, v11, v11
	v_mul_f32_e32 v24, v13, v13
	v_fmac_f32_e32 v23, v10, v10
	v_fmac_f32_e32 v24, v12, v12
	v_add_f32_e32 v23, v23, v24
	v_add_f32_e32 v22, v22, v23
	s_waitcnt vmcnt(4)
	v_mul_f32_e32 v23, v15, v15
	v_mul_f32_e32 v24, v17, v17
	v_fmac_f32_e32 v23, v14, v14
	v_fmac_f32_e32 v24, v16, v16
	v_add_f32_e32 v23, v23, v24
	v_add_f32_e32 v22, v22, v23
	s_lshl_b64 s[16:17], s[14:15], 11
	v_lshl_add_u64 v[24:25], v[20:21], 0, s[16:17]
	v_add_f32_dpp v22, v22, v22 row_ror:8 row_mask:0xf bank_mask:0xf bound_ctrl:1
	v_cvt_pk_bf16_f32 v2, v2, v3
	v_cvt_pk_bf16_f32 v3, v4, v5
	global_store_dwordx2 v[24:25], v[2:3], off sc1
	v_cvt_pk_bf16_f32 v2, v6, v7
	v_cvt_pk_bf16_f32 v3, v8, v9
	s_nop 0
	v_add_f32_dpp v22, v22, v22 row_ror:4 row_mask:0xf bank_mask:0xf bound_ctrl:1
	global_store_dwordx2 v[24:25], v[2:3], off offset:512 sc1
	v_cvt_pk_bf16_f32 v2, v10, v11
	v_cvt_pk_bf16_f32 v3, v12, v13
	global_store_dwordx2 v[24:25], v[2:3], off offset:1024 sc1
	v_add_f32_dpp v22, v22, v22 row_ror:2 row_mask:0xf bank_mask:0xf bound_ctrl:1
	v_cvt_pk_bf16_f32 v2, v14, v15
	v_cvt_pk_bf16_f32 v3, v16, v17
	global_store_dwordx2 v[24:25], v[2:3], off offset:1536 sc1
	s_nop 0
	v_add_f32_dpp v22, v22, v22 row_ror:1 row_mask:0xf bank_mask:0xf bound_ctrl:1
	v_mov_b32_e32 v23, v22
	s_nop 1
	v_permlane16_swap_b32_e32 v22, v23
	v_add_f32_e32 v22, v22, v23
	v_mov_b32_e32 v23, v22
	s_nop 1
	v_permlane32_swap_b32_e32 v22, v23
	s_and_saveexec_b64 s[16:17], vcc
	s_cbranch_execz .LBB0_93
	s_ashr_i32 s18, s14, 12
	s_ashr_i32 s19, s18, 31
	s_and_b32 s15, s14, 0xfff
	s_lshl_b64 s[18:19], s[18:19], 18
	s_add_u32 s18, s11, s18
	s_addc_u32 s19, s20, s19
	s_lshl_b32 s15, s15, 2
	v_add_f32_e32 v2, v22, v23
	v_mov_b32_e32 v3, s15
	global_store_dword v3, v2, s[18:19]
	s_branch .LBB0_93

.LBB0_100:
	v_mul_hi_i32 v7, v6, s18
	v_add_u32_e32 v7, v7, v6
	v_lshrrev_b32_e32 v8, 31, v7
	v_ashrrev_i32_e32 v7, 13, v7
	v_add_u32_e32 v8, v7, v8
	v_mul_i32_i24_e32 v7, 0x3c00, v8
	v_ashrrev_i32_e32 v9, 31, v8
	v_sub_u32_e32 v10, v6, v7
	v_lshlrev_b64 v[8:9], 18, v[8:9]
	v_add_u32_e32 v6, s11, v6
	s_waitcnt lgkmcnt(0)
	v_lshl_add_u64 v[8:9], s[4:5], 0, v[8:9]
	v_ashrrev_i32_e32 v11, 31, v10
	v_cmp_lt_i32_e32 vcc, s19, v6
	v_lshl_add_u64 v[8:9], v[10:11], 4, v[8:9]
	s_or_b64 s[16:17], vcc, s[16:17]
	v_add_co_u32_e32 v8, vcc, 0x104000, v8
	s_nop 1
	v_addc_co_u32_e32 v9, vcc, 0, v9, vcc
	global_store_dwordx4 v[8:9], v[2:5], off sc1
	s_andn2_b64 exec, exec, s[16:17]
	s_cbranch_execnz .LBB0_100

.LBB0_103:
	s_mov_b32 s16, 1
	s_ashr_i32 s17, s16, 31
	s_lshl_b64 s[16:17], s[16:17], 3
	s_add_u32 s16, s0, s16
	s_addc_u32 s17, s1, s17
	s_load_dwordx2 s[16:17], s[16:17], 0x0
	s_mov_b32 s4, 2
	s_ashr_i32 s5, s4, 31
	s_lshl_b64 s[4:5], s[4:5], 3
	s_waitcnt lgkmcnt(0)
	v_lshl_add_u64 v[24:25], s[16:17], 0, v[2:3]
	global_load_dwordx4 v[8:11], v[24:25], off
	global_load_dwordx4 v[12:15], v[24:25], off offset:1024
	global_load_dwordx4 v[16:19], v[24:25], off offset:2048
	global_load_dwordx4 v[20:23], v[24:25], off offset:3072
	s_add_u32 s4, s0, s4
	s_addc_u32 s5, s1, s5
	s_load_dwordx2 s[16:17], s[4:5], 0x0
	s_mov_b32 s18, 0
	s_ashr_i32 s19, s18, 31
	s_lshl_b64 s[4:5], s[18:19], 3
	s_waitcnt lgkmcnt(0)
	global_load_dwordx4 v[24:27], v4, s[16:17]
	s_add_u32 s4, s0, s4
	s_addc_u32 s5, s1, s5
	s_load_dwordx2 s[4:5], s[4:5], 0xd0
	s_ashr_i32 s18, s12, 8
	s_ashr_i32 s19, s18, 31
	s_lshl_b64 s[18:19], s[18:19], 24
	v_lshl_add_u64 v[2:3], v[2:3], 0, s[14:15]
	s_waitcnt lgkmcnt(0)
	s_add_u32 s4, s4, s18
	s_addc_u32 s5, s5, s19
	s_and_b32 s13, s20, 0x3fc00
	s_lshl_b32 s13, s13, 1
	s_add_u32 s18, s4, s13
	s_addc_u32 s19, s5, 0
	s_add_i32 s12, s12, s10
	s_add_i32 s20, s20, s21
	s_cmpk_lt_i32 s12, 0x400
	s_waitcnt vmcnt(4)
	v_mul_f32_e32 v28, v9, v9
	v_mul_f32_e32 v29, v11, v11
	s_waitcnt vmcnt(3)
	v_mul_f32_e32 v30, v13, v13
	v_mul_f32_e32 v31, v15, v15
	s_waitcnt vmcnt(2)
	v_mul_f32_e32 v32, v17, v17
	v_mul_f32_e32 v33, v19, v19
	v_fmac_f32_e32 v28, v8, v8
	v_fmac_f32_e32 v29, v10, v10
	v_fmac_f32_e32 v30, v12, v12
	v_fmac_f32_e32 v31, v14, v14
	s_waitcnt vmcnt(1)
	v_mul_f32_e32 v34, v21, v21
	v_mul_f32_e32 v35, v23, v23
	v_fmac_f32_e32 v32, v16, v16
	v_fmac_f32_e32 v33, v18, v18
	v_add_f32_e32 v28, v28, v29
	v_add_f32_e32 v29, v30, v31
	v_fmac_f32_e32 v34, v20, v20
	v_fmac_f32_e32 v35, v22, v22
	v_add_f32_e32 v30, v32, v33
	v_add_f32_e32 v28, v28, v29
	v_add_f32_e32 v31, v34, v35
	v_add_f32_e32 v28, v28, v30
	v_add_f32_e32 v28, v28, v31
	s_nop 1
	v_add_f32_dpp v28, v28, v28 row_ror:8 row_mask:0xf bank_mask:0xf bound_ctrl:1
	s_nop 1
	v_add_f32_dpp v28, v28, v28 row_ror:4 row_mask:0xf bank_mask:0xf bound_ctrl:1
	s_nop 1
	v_add_f32_dpp v28, v28, v28 row_ror:2 row_mask:0xf bank_mask:0xf bound_ctrl:1
	s_nop 1
	v_add_f32_dpp v28, v28, v28 row_ror:1 row_mask:0xf bank_mask:0xf bound_ctrl:1
	v_mov_b32_e32 v29, v28
	s_nop 1
	v_permlane16_swap_b32_e32 v28, v29
	v_add_f32_e32 v28, v28, v29
	v_mov_b32_e32 v29, v28
	s_nop 1
	v_permlane32_swap_b32_e32 v28, v29
	v_add_f32_e32 v28, v28, v29
	v_fmamk_f32 v28, v28, 0x3a800000, v5
	v_mul_f32_e32 v29, 0x4f800000, v28
	v_cmp_gt_f32_e32 vcc, s11, v28
	s_nop 1
	v_cndmask_b32_e32 v28, v28, v29, vcc
	v_sqrt_f32_e32 v29, v28
	s_nop 0
	v_add_u32_e32 v30, -1, v29
	v_add_u32_e32 v31, 1, v29
	v_fma_f32 v32, -v30, v29, v28
	v_fma_f32 v33, -v31, v29, v28
	v_cmp_ge_f32_e64 s[4:5], 0, v32
	s_nop 1
	v_cndmask_b32_e64 v29, v29, v30, s[4:5]
	v_cmp_lt_f32_e64 s[4:5], 0, v33
	s_nop 1
	v_cndmask_b32_e64 v29, v29, v31, s[4:5]
	v_mul_f32_e32 v30, 0x37800000, v29
	v_cndmask_b32_e32 v29, v29, v30, vcc
	v_cmp_class_f32_e32 vcc, v28, v6
	s_nop 1
	v_cndmask_b32_e32 v28, v29, v28, vcc
	v_div_scale_f32 v29, s[4:5], v28, v28, 1.0
	v_rcp_f32_e32 v31, v29
	v_div_scale_f32 v30, vcc, 1.0, v28, 1.0
	v_fma_f32 v32, -v29, v31, 1.0
	v_fmac_f32_e32 v31, v32, v31
	v_mul_f32_e32 v32, v30, v31
	v_fma_f32 v33, -v29, v32, v30
	v_fmac_f32_e32 v32, v33, v31
	v_fma_f32 v29, -v29, v32, v30
	v_div_fmas_f32 v29, v29, v31, v32
	v_div_fixup_f32 v28, v29, v28, 1.0
	v_mul_f32_e32 v8, v8, v28
	v_mul_f32_e32 v9, v9, v28
	v_mul_f32_e32 v10, v10, v28
	v_mul_f32_e32 v11, v11, v28
	s_waitcnt vmcnt(0)
	v_mul_f32_e32 v8, v24, v8
	v_mul_f32_e32 v9, v25, v9
	v_mul_f32_e32 v10, v26, v10
	v_mul_f32_e32 v11, v27, v11
	v_cvt_pk_bf16_f32 v8, v8, v9
	v_cvt_pk_bf16_f32 v9, v10, v11
	global_store_dwordx2 v7, v[8:9], s[18:19] sc1
	global_load_dwordx4 v[8:11], v4, s[16:17] offset:1024
	v_mul_f32_e32 v12, v12, v28
	v_mul_f32_e32 v13, v13, v28
	v_mul_f32_e32 v14, v14, v28
	v_mul_f32_e32 v15, v15, v28
	s_waitcnt vmcnt(0)
	v_mul_f32_e32 v8, v12, v8
	v_mul_f32_e32 v9, v13, v9
	v_mul_f32_e32 v10, v14, v10
	v_mul_f32_e32 v11, v15, v11
	v_cvt_pk_bf16_f32 v8, v8, v9
	v_cvt_pk_bf16_f32 v9, v10, v11
	global_store_dwordx2 v7, v[8:9], s[18:19] offset:512 sc1
	global_load_dwordx4 v[8:11], v4, s[16:17] offset:2048
	v_mul_f32_e32 v12, v16, v28
	v_mul_f32_e32 v13, v17, v28
	v_mul_f32_e32 v14, v18, v28
	v_mul_f32_e32 v15, v19, v28
	s_waitcnt vmcnt(0)
	v_mul_f32_e32 v8, v12, v8
	v_mul_f32_e32 v9, v13, v9
	v_mul_f32_e32 v10, v14, v10
	v_mul_f32_e32 v11, v15, v11
	v_cvt_pk_bf16_f32 v8, v8, v9
	v_cvt_pk_bf16_f32 v9, v10, v11
	global_store_dwordx2 v7, v[8:9], s[18:19] offset:1024 sc1
	global_load_dwordx4 v[8:11], v4, s[16:17] offset:3072
	v_mul_f32_e32 v12, v20, v28
	v_mul_f32_e32 v13, v21, v28
	v_mul_f32_e32 v14, v22, v28
	v_mul_f32_e32 v15, v23, v28
	s_waitcnt vmcnt(0)
	v_mul_f32_e32 v8, v12, v8
	v_mul_f32_e32 v9, v13, v9
	v_mul_f32_e32 v10, v14, v10
	v_mul_f32_e32 v11, v15, v11
	v_cvt_pk_bf16_f32 v8, v8, v9
	v_cvt_pk_bf16_f32 v9, v10, v11
	global_store_dwordx2 v7, v[8:9], s[18:19] offset:1536 sc1
	s_cbranch_scc1 .LBB0_103

.LBB0_180:
	ds_write2_b32 v23, v15, v24 offset1:66
	ds_write2_b32 v23, v25, v26 offset0:132 offset1:198
	ds_write2_b32 v55, v27, v28 offset0:8 offset1:74
	ds_write2_b32 v55, v29, v30 offset0:140 offset1:206
	ds_write2_b32 v56, v31, v32 offset0:16 offset1:82
	ds_write2_b32 v56, v33, v34 offset0:148 offset1:214
	ds_write2_b32 v57, v35, v36 offset0:24 offset1:90
	ds_write2_b32 v57, v37, v38 offset0:156 offset1:222
	ds_write2_b32 v58, v39, v40 offset0:32 offset1:98
	ds_write2_b32 v58, v41, v42 offset0:164 offset1:230
	ds_write2_b32 v59, v43, v44 offset0:40 offset1:106
	ds_write2_b32 v59, v45, v46 offset0:172 offset1:238
	ds_write2_b32 v60, v54, v53 offset0:48 offset1:114
	ds_write2_b32 v60, v52, v51 offset0:180 offset1:246
	ds_write2_b32 v61, v50, v49 offset0:56 offset1:122
	ds_write2_b32 v61, v48, v47 offset0:188 offset1:254
	s_waitcnt lgkmcnt(0)
	ds_read2_b32 v[60:61], v19 offset1:8
	ds_read2_b32 v[62:63], v19 offset0:33 offset1:41
	ds_read2_b32 v[64:65], v19 offset0:66 offset1:74
	ds_read2_b32 v[66:67], v19 offset0:99 offset1:107
	ds_read2_b32 v[68:69], v19 offset0:132 offset1:140
	ds_read2_b32 v[70:71], v19 offset0:165 offset1:173
	ds_read2_b32 v[72:73], v19 offset0:198 offset1:206
	ds_read2_b32 v[74:75], v19 offset0:231 offset1:239
	s_mul_i32 s15, s15, s14
	s_waitcnt vmcnt(0) lgkmcnt(7)
	v_mul_f32_e32 v55, v6, v60
	s_waitcnt lgkmcnt(6)
	v_mul_f32_e32 v56, v7, v62
	s_sub_i32 s4, s4, s15
	v_cvt_pk_bf16_f32 v56, v55, v56
	s_waitcnt lgkmcnt(5)
	v_mul_f32_e32 v55, v8, v64
	s_waitcnt lgkmcnt(4)
	v_mul_f32_e32 v57, v9, v66
	s_sext_i32_i16 s14, s4
	v_cvt_pk_bf16_f32 v57, v55, v57
	s_waitcnt lgkmcnt(3)
	v_mul_f32_e32 v55, v2, v68
	s_waitcnt lgkmcnt(2)
	v_mul_f32_e32 v58, v3, v70
	s_lshl_b32 s16, s14, 5
	v_cvt_pk_bf16_f32 v58, v55, v58
	s_waitcnt lgkmcnt(1)
	v_mul_f32_e32 v55, v4, v72
	s_waitcnt lgkmcnt(0)
	v_mul_f32_e32 v59, v5, v74
	v_cvt_pk_bf16_f32 v59, v55, v59
	v_or_b32_e32 v55, s16, v18
	v_mad_u64_u32 v[76:77], s[14:15], v55, s17, 0
	s_bfe_i64 s[14:15], s[4:5], 0x100000
	s_mul_i32 s4, s15, s17
	v_add_u32_e32 v77, s4, v77
	v_lshl_add_u64 v[76:77], v[76:77], 1, s[22:23]
	s_lshl_b64 s[12:13], s[12:13], 1
	v_lshl_add_u64 v[76:77], v[76:77], 0, s[12:13]
	v_lshl_add_u64 v[76:77], v[76:77], 0, v[10:11]
	global_store_dwordx4 v[76:77], v[56:59], off sc1
	v_mul_f32_e32 v55, v6, v61
	s_nop 0
	v_mul_f32_e32 v56, v7, v63
	v_cvt_pk_bf16_f32 v56, v55, v56
	v_mul_f32_e32 v55, v8, v65
	v_mul_f32_e32 v57, v9, v67
	v_cvt_pk_bf16_f32 v57, v55, v57
	v_mul_f32_e32 v55, v2, v69
	v_mul_f32_e32 v58, v3, v71
	v_cvt_pk_bf16_f32 v58, v55, v58
	v_mul_f32_e32 v55, v4, v73
	v_mul_f32_e32 v59, v5, v75
	v_cvt_pk_bf16_f32 v59, v55, v59
	v_or_b32_e32 v55, s16, v20
	v_mad_u64_u32 v[60:61], s[14:15], v55, s17, 0
	v_add_u32_e32 v61, s4, v61
	v_lshl_add_u64 v[60:61], v[60:61], 1, s[22:23]
	v_lshl_add_u64 v[60:61], v[60:61], 0, s[12:13]
	v_lshl_add_u64 v[60:61], v[60:61], 0, v[10:11]
	ds_read2_b32 v[62:63], v19 offset0:16 offset1:24
	ds_read2_b32 v[64:65], v19 offset0:49 offset1:57
	global_store_dwordx4 v[60:61], v[56:59], off sc1
	ds_read2_b32 v[60:61], v19 offset0:82 offset1:90
	ds_read2_b32 v[66:67], v19 offset0:115 offset1:123
	ds_read2_b32 v[68:69], v19 offset0:148 offset1:156
	ds_read2_b32 v[70:71], v19 offset0:181 offset1:189
	ds_read2_b32 v[72:73], v19 offset0:214 offset1:222
	ds_read2_b32 v[74:75], v19 offset0:247 offset1:255
	s_waitcnt lgkmcnt(7)
	v_mul_f32_e32 v55, v6, v62
	s_waitcnt lgkmcnt(6)
	v_mul_f32_e32 v56, v7, v64
	v_cvt_pk_bf16_f32 v56, v55, v56
	s_waitcnt lgkmcnt(5)
	v_mul_f32_e32 v55, v8, v60
	s_waitcnt lgkmcnt(4)
	v_mul_f32_e32 v57, v9, v66
	v_mul_f32_e32 v6, v6, v63
	v_mul_f32_e32 v7, v7, v65
	v_cvt_pk_bf16_f32 v57, v55, v57
	s_waitcnt lgkmcnt(3)
	v_mul_f32_e32 v55, v2, v68
	s_waitcnt lgkmcnt(2)
	v_mul_f32_e32 v58, v3, v70
	v_cvt_pk_bf16_f32 v6, v6, v7
	v_mul_f32_e32 v7, v8, v61
	v_mul_f32_e32 v8, v9, v67
	v_mul_f32_e32 v2, v2, v69
	v_cvt_pk_bf16_f32 v58, v55, v58
	s_waitcnt lgkmcnt(1)
	v_mul_f32_e32 v55, v4, v72
	s_waitcnt lgkmcnt(0)
	v_mul_f32_e32 v59, v5, v74
	v_cvt_pk_bf16_f32 v7, v7, v8
	v_mul_f32_e32 v3, v3, v71
	v_cvt_pk_bf16_f32 v8, v2, v3
	v_mul_f32_e32 v2, v4, v73
	v_cvt_pk_bf16_f32 v59, v55, v59
	v_or_b32_e32 v55, s16, v21
	v_mul_f32_e32 v3, v5, v75
	v_cvt_pk_bf16_f32 v9, v2, v3
	v_or_b32_e32 v2, s16, v22
	v_mad_u64_u32 v[76:77], s[14:15], v55, s17, 0
	v_mad_u64_u32 v[2:3], s[14:15], v2, s17, 0
	v_add_u32_e32 v77, s4, v77
	v_add_u32_e32 v3, s4, v3
	v_lshl_add_u64 v[76:77], v[76:77], 1, s[22:23]
	v_lshl_add_u64 v[2:3], v[2:3], 1, s[22:23]
	v_lshl_add_u64 v[76:77], v[76:77], 0, s[12:13]
	v_lshl_add_u64 v[2:3], v[2:3], 0, s[12:13]
	v_lshl_add_u64 v[76:77], v[76:77], 0, v[10:11]
	v_lshl_add_u64 v[2:3], v[2:3], 0, v[10:11]
	global_store_dwordx4 v[76:77], v[56:59], off sc1
	global_store_dwordx4 v[2:3], v[6:9], off sc1
	s_waitcnt lgkmcnt(0)

.LBB0_249:
	s_waitcnt vmcnt(30)
	ds_write2_b32 v23, v55, v56 offset1:66
	s_waitcnt vmcnt(28)
	ds_write2_b32 v23, v57, v59 offset0:132 offset1:198
	v_add_u32_e32 v55, 0x400, v23
	s_waitcnt vmcnt(26)
	ds_write2_b32 v55, v58, v60 offset0:8 offset1:74
	s_waitcnt vmcnt(24)
	ds_write2_b32 v55, v61, v62 offset0:140 offset1:206
	v_add_u32_e32 v56, 0x800, v23
	v_add_u32_e32 v57, 0xc00, v23
	v_add_u32_e32 v58, 0x1000, v23
	v_add_u32_e32 v59, 0x1400, v23
	v_add_u32_e32 v60, 0x1800, v23
	v_add_u32_e32 v61, 0x1c00, v23
	s_waitcnt vmcnt(22)
	ds_write2_b32 v56, v63, v64 offset0:16 offset1:82
	s_waitcnt vmcnt(20)
	ds_write2_b32 v56, v65, v67 offset0:148 offset1:214
	s_waitcnt vmcnt(18)
	ds_write2_b32 v57, v66, v68 offset0:24 offset1:90
	s_waitcnt vmcnt(16)
	ds_write2_b32 v57, v69, v70 offset0:156 offset1:222
	s_waitcnt vmcnt(14)
	ds_write2_b32 v58, v71, v72 offset0:32 offset1:98
	s_waitcnt vmcnt(12)
	ds_write2_b32 v58, v73, v75 offset0:164 offset1:230
	s_waitcnt vmcnt(10)
	ds_write2_b32 v59, v74, v76 offset0:40 offset1:106
	s_waitcnt vmcnt(8)
	ds_write2_b32 v59, v77, v78 offset0:172 offset1:238
	s_waitcnt vmcnt(6)
	ds_write2_b32 v60, v79, v80 offset0:48 offset1:114
	s_waitcnt vmcnt(4)
	ds_write2_b32 v60, v81, v83 offset0:180 offset1:246
	s_waitcnt vmcnt(2)
	ds_write2_b32 v61, v82, v84 offset0:56 offset1:122
	s_waitcnt vmcnt(0)
	ds_write2_b32 v61, v85, v86 offset0:188 offset1:254
	s_waitcnt lgkmcnt(0)
	ds_read2_b32 v[66:67], v19 offset1:8
	ds_read2_b32 v[68:69], v19 offset0:33 offset1:41
	ds_read2_b32 v[70:71], v19 offset0:66 offset1:74
	ds_read2_b32 v[72:73], v19 offset0:99 offset1:107
	ds_read2_b32 v[74:75], v19 offset0:132 offset1:140
	ds_read2_b32 v[76:77], v19 offset0:165 offset1:173
	ds_read2_b32 v[78:79], v19 offset0:198 offset1:206
	ds_read2_b32 v[80:81], v19 offset0:231 offset1:239
	s_waitcnt lgkmcnt(7)
	v_mul_f32_e32 v62, v6, v66
	s_waitcnt lgkmcnt(6)
	v_mul_f32_e32 v63, v7, v68
	v_cvt_pk_bf16_f32 v62, v62, v63
	s_waitcnt lgkmcnt(5)
	v_mul_f32_e32 v63, v8, v70
	s_waitcnt lgkmcnt(4)
	v_mul_f32_e32 v64, v9, v72
	v_cvt_pk_bf16_f32 v63, v63, v64
	s_waitcnt lgkmcnt(3)
	v_mul_f32_e32 v64, v2, v74
	s_waitcnt lgkmcnt(2)
	v_mul_f32_e32 v65, v3, v76
	v_cvt_pk_bf16_f32 v64, v64, v65
	s_waitcnt lgkmcnt(1)
	v_mul_f32_e32 v65, v4, v78
	s_waitcnt lgkmcnt(0)
	v_mul_f32_e32 v66, v5, v80
	v_cvt_pk_bf16_f32 v65, v65, v66
	v_or_b32_e32 v66, s16, v18
	v_mul_hi_i32_i24_e32 v83, s55, v66
	v_mul_i32_i24_e32 v82, s55, v66
	v_lshl_add_u64 v[82:83], v[82:83], 1, s[12:13]
	s_lshl_b64 s[14:15], s[18:19], 1
	v_lshl_add_u64 v[82:83], v[82:83], 0, s[14:15]
	v_lshl_add_u64 v[82:83], v[82:83], 0, v[10:11]
	global_store_dwordx4 v[82:83], v[62:65], off sc1
	v_mul_f32_e32 v66, v5, v81
	s_andn2_b64 vcc, exec, s[20:21]
	v_mul_f32_e32 v62, v6, v67
	v_mul_f32_e32 v63, v7, v69
	v_cvt_pk_bf16_f32 v62, v62, v63
	v_mul_f32_e32 v63, v8, v71
	v_mul_f32_e32 v64, v9, v73
	v_cvt_pk_bf16_f32 v63, v63, v64
	v_mul_f32_e32 v64, v2, v75
	v_mul_f32_e32 v65, v3, v77
	v_cvt_pk_bf16_f32 v64, v64, v65
	v_mul_f32_e32 v65, v4, v79
	v_cvt_pk_bf16_f32 v65, v65, v66
	v_or_b32_e32 v66, s16, v20
	v_mul_hi_i32_i24_e32 v67, s55, v66
	v_mul_i32_i24_e32 v66, s55, v66
	v_lshl_add_u64 v[66:67], v[66:67], 1, s[12:13]
	v_lshl_add_u64 v[66:67], v[66:67], 0, s[14:15]
	v_lshl_add_u64 v[66:67], v[66:67], 0, v[10:11]
	ds_read2_b32 v[68:69], v19 offset0:16 offset1:24
	ds_read2_b32 v[70:71], v19 offset0:49 offset1:57
	global_store_dwordx4 v[66:67], v[62:65], off sc1
	ds_read2_b32 v[66:67], v19 offset0:82 offset1:90
	ds_read2_b32 v[72:73], v19 offset0:115 offset1:123
	ds_read2_b32 v[74:75], v19 offset0:148 offset1:156
	ds_read2_b32 v[76:77], v19 offset0:181 offset1:189
	ds_read2_b32 v[78:79], v19 offset0:214 offset1:222
	ds_read2_b32 v[80:81], v19 offset0:247 offset1:255
	s_waitcnt lgkmcnt(7)
	v_mul_f32_e32 v62, v6, v68
	s_waitcnt lgkmcnt(6)
	v_mul_f32_e32 v63, v7, v70
	v_cvt_pk_bf16_f32 v62, v62, v63
	s_waitcnt lgkmcnt(5)
	v_mul_f32_e32 v63, v8, v66
	s_waitcnt lgkmcnt(4)
	v_mul_f32_e32 v64, v9, v72
	v_mul_f32_e32 v6, v6, v69
	v_mul_f32_e32 v7, v7, v71
	v_cvt_pk_bf16_f32 v63, v63, v64
	s_waitcnt lgkmcnt(3)
	v_mul_f32_e32 v64, v2, v74
	s_waitcnt lgkmcnt(2)
	v_mul_f32_e32 v65, v3, v76
	v_cvt_pk_bf16_f32 v6, v6, v7
	v_mul_f32_e32 v7, v8, v67
	v_mul_f32_e32 v8, v9, v73
	v_mul_f32_e32 v2, v2, v75
	v_cvt_pk_bf16_f32 v64, v64, v65
	s_waitcnt lgkmcnt(1)
	v_mul_f32_e32 v65, v4, v78
	s_waitcnt lgkmcnt(0)
	v_mul_f32_e32 v66, v5, v80
	v_cvt_pk_bf16_f32 v7, v7, v8
	v_mul_f32_e32 v3, v3, v77
	v_cvt_pk_bf16_f32 v8, v2, v3
	v_mul_f32_e32 v2, v4, v79
	v_cvt_pk_bf16_f32 v65, v65, v66
	v_or_b32_e32 v66, s16, v21
	v_mul_f32_e32 v3, v5, v81
	v_cvt_pk_bf16_f32 v9, v2, v3
	v_or_b32_e32 v2, s16, v22
	v_mul_hi_i32_i24_e32 v83, s55, v66
	v_mul_i32_i24_e32 v82, s55, v66
	v_mul_hi_i32_i24_e32 v3, s55, v2
	v_mul_i32_i24_e32 v2, s55, v2
	v_lshl_add_u64 v[82:83], v[82:83], 1, s[12:13]
	v_lshl_add_u64 v[2:3], v[2:3], 1, s[12:13]
	v_lshl_add_u64 v[82:83], v[82:83], 0, s[14:15]
	v_lshl_add_u64 v[2:3], v[2:3], 0, s[14:15]
	v_lshl_add_u64 v[82:83], v[82:83], 0, v[10:11]
	v_lshl_add_u64 v[2:3], v[2:3], 0, v[10:11]
	global_store_dwordx4 v[82:83], v[62:65], off sc1
	global_store_dwordx4 v[2:3], v[6:9], off sc1
	s_waitcnt lgkmcnt(0)
	s_cbranch_vccnz .LBB0_181
	s_lshr_b32 s14, s56, 5
	v_cvt_f32_i32_e32 v2, s14
	s_sext_i32_i16 s12, s4
	v_cvt_f32_i32_e32 v3, s12
	s_ashr_i32 s12, s12, 30
	v_rcp_iflag_f32_e32 v4, v2
	s_or_b32 s15, s12, 1
	v_mul_f32_e32 v4, v3, v4
	v_trunc_f32_e32 v4, v4
	v_fma_f32 v3, -v4, v2, v3
	v_cvt_i32_f32_e32 v4, v4
	v_cmp_ge_f32_e64 s[12:13], |v3|, v2
	s_and_b64 s[12:13], s[12:13], exec
	s_cselect_b32 s12, s15, 0
	v_readfirstlane_b32 s15, v4
	s_add_i32 s15, s15, s12
	s_sext_i32_i16 s12, s15
	s_lshl_b32 s12, s12, 6
	s_ashr_i32 s13, s12, 31
	s_cmp_eq_u64 s[24:25], 0
	s_cbranch_scc0 .LBB0_179
	v_mov_b32_e32 v2, 1.0
	v_mov_b32_e32 v3, 1.0
	v_mov_b32_e32 v4, 1.0
	v_mov_b32_e32 v5, 1.0
	v_mov_b32_e32 v6, 1.0
	v_mov_b32_e32 v7, 1.0
	v_mov_b32_e32 v8, 1.0
	v_mov_b32_e32 v9, 1.0
	s_branch .LBB0_180
